# seam barrier: L1 invalidate issued at arrival instead of after release; non-leader workgroups poll the cross-XCC generation word directly
# baseline (speedup 1.0000x reference)
.Ls0_169:
	s_or_b64 exec, exec, s[26:27]
	v_cvt_f32_u32_e32 v4, v2
	s_waitcnt vmcnt(0)
	buffer_inv sc1
	v_readfirstlane_b32 s10, v3
	v_sub_u32_e32 v3, 0, v2
	v_rcp_iflag_f32_e32 v4, v4
	v_add_u32_e32 v5, s10, v1
	v_mul_f32_e32 v4, 0x4f7ffffe, v4
	v_cvt_u32_f32_e32 v4, v4
	v_mul_lo_u32 v1, v3, v4
	v_mul_hi_u32 v1, v4, v1
	v_add_u32_e32 v1, v4, v1
	v_mul_hi_u32 v1, v5, v1
	v_mul_lo_u32 v3, v1, v2
	v_sub_u32_e32 v3, v5, v3
	v_add_u32_e32 v4, 1, v1
	v_cmp_ge_u32_e32 vcc, v3, v2
	s_nop 1
	v_cndmask_b32_e32 v1, v1, v4, vcc
	v_sub_u32_e32 v4, v3, v2
	v_cndmask_b32_e32 v3, v3, v4, vcc
	v_add_u32_e32 v4, 1, v1
	v_cmp_ge_u32_e32 vcc, v3, v2
	v_add_u32_e32 v3, 1, v5
	s_nop 0
	v_cndmask_b32_e32 v1, v1, v4, vcc
	v_mul_lo_u32 v4, v2, v1
	v_add_u32_e32 v2, v4, v2
	v_cmp_ne_u32_e32 vcc, v3, v2
	s_and_saveexec_b64 s[10:11], vcc
	s_xor_b64 s[10:11], exec, s[10:11]
	s_cbranch_execz .Ls0_183
	s_waitcnt lgkmcnt(0)
	s_add_u32 s38, s30, 0x4500
	s_addc_u32 s39, s31, 0
	v_mov_b32_e32 v0, 0
	global_load_dword v0, v0, s[38:39] sc1
	s_waitcnt vmcnt(0)
	v_cmp_eq_u32_e32 vcc, v0, v1
	s_and_saveexec_b64 s[26:27], vcc
	s_cbranch_execz .Ls0_182
	s_add_u32 s36, s30, 0x1200
	s_addc_u32 s37, s31, 0
	s_mov_b32 s52, 1
	s_mov_b64 s[42:43], 0
	v_mov_b32_e32 v0, 0
	s_branch .Ls0_173

.Ls0_182:
	s_or_b64 exec, exec, s[26:27]
	s_waitcnt vmcnt(0)
	s_waitcnt vmcnt(0)

.Ls0_200:
	s_or_b64 exec, exec, s[10:11]
	s_mov_b64 s[10:11], exec
	v_mbcnt_lo_u32_b32 v0, s10, 0
	v_mbcnt_hi_u32_b32 v0, s11, v0
	v_cmp_eq_u32_e32 vcc, 0, v0
	s_waitcnt vmcnt(0)
	s_and_saveexec_b64 s[26:27], vcc
	s_cbranch_execz .Ls0_202
	s_bcnt1_i32_b64 s10, s[10:11]
	v_mov_b32_e32 v0, 0x2000
	v_mov_b32_e32 v1, s10
	global_atomic_add v0, v1, s[6:7] offset:1024

.LBB0_268:
	s_or_b64 exec, exec, s[26:27]
	v_cvt_f32_u32_e32 v4, v2
	s_waitcnt vmcnt(0)
	buffer_inv sc1
	v_readfirstlane_b32 s10, v3
	v_sub_u32_e32 v3, 0, v2
	v_rcp_iflag_f32_e32 v4, v4
	v_add_u32_e32 v5, s10, v1
	v_mul_f32_e32 v4, 0x4f7ffffe, v4
	v_cvt_u32_f32_e32 v4, v4
	v_mul_lo_u32 v1, v3, v4
	v_mul_hi_u32 v1, v4, v1
	v_add_u32_e32 v1, v4, v1
	v_mul_hi_u32 v1, v5, v1
	v_mul_lo_u32 v3, v1, v2
	v_sub_u32_e32 v3, v5, v3
	v_add_u32_e32 v4, 1, v1
	v_cmp_ge_u32_e32 vcc, v3, v2
	s_nop 1
	v_cndmask_b32_e32 v1, v1, v4, vcc
	v_sub_u32_e32 v4, v3, v2
	v_cndmask_b32_e32 v3, v3, v4, vcc
	v_add_u32_e32 v4, 1, v1
	v_cmp_ge_u32_e32 vcc, v3, v2
	v_add_u32_e32 v3, 1, v5
	s_nop 0
	v_cndmask_b32_e32 v1, v1, v4, vcc
	v_mul_lo_u32 v4, v2, v1
	v_add_u32_e32 v2, v4, v2
	v_cmp_ne_u32_e32 vcc, v3, v2
	s_and_saveexec_b64 s[10:11], vcc
	s_xor_b64 s[10:11], exec, s[10:11]
	s_cbranch_execz .LBB0_282
	s_waitcnt lgkmcnt(0)
	s_add_u32 s38, s30, 0x4500
	s_addc_u32 s39, s31, 0
	v_mov_b32_e32 v0, 0
	global_load_dword v0, v0, s[38:39] sc1
	s_waitcnt vmcnt(0)
	v_cmp_eq_u32_e32 vcc, v0, v1
	s_and_saveexec_b64 s[26:27], vcc
	s_cbranch_execz .LBB0_281
	s_add_u32 s36, s30, 0x1200
	s_addc_u32 s37, s31, 0
	s_mov_b32 s52, 1
	s_mov_b64 s[40:41], 0
	v_mov_b32_e32 v0, 0
	s_branch .LBB0_272

.LBB0_299:
	s_or_b64 exec, exec, s[10:11]
	s_mov_b64 s[10:11], exec
	v_mbcnt_lo_u32_b32 v0, s10, 0
	v_mbcnt_hi_u32_b32 v0, s11, v0
	v_cmp_eq_u32_e32 vcc, 0, v0
	s_waitcnt vmcnt(0)
	s_and_saveexec_b64 s[26:27], vcc
	s_cbranch_execz .LBB0_301
	s_bcnt1_i32_b64 s10, s[10:11]
	v_mov_b32_e32 v0, 0x2000
	v_mov_b32_e32 v1, s10
	global_atomic_add v0, v1, s[8:9] offset:1024

.LBB0_353:
	s_or_b64 exec, exec, s[26:27]
	v_cvt_f32_u32_e32 v4, v2
	s_waitcnt vmcnt(0)
	buffer_inv sc1
	v_readfirstlane_b32 s10, v3
	v_sub_u32_e32 v3, 0, v2
	v_rcp_iflag_f32_e32 v4, v4
	v_add_u32_e32 v5, s10, v1
	v_mul_f32_e32 v4, 0x4f7ffffe, v4
	v_cvt_u32_f32_e32 v4, v4
	v_mul_lo_u32 v1, v3, v4
	v_mul_hi_u32 v1, v4, v1
	v_add_u32_e32 v1, v4, v1
	v_mul_hi_u32 v1, v5, v1
	v_mul_lo_u32 v3, v1, v2
	v_sub_u32_e32 v3, v5, v3
	v_add_u32_e32 v4, 1, v1
	v_cmp_ge_u32_e32 vcc, v3, v2
	s_nop 1
	v_cndmask_b32_e32 v1, v1, v4, vcc
	v_sub_u32_e32 v4, v3, v2
	v_cndmask_b32_e32 v3, v3, v4, vcc
	v_add_u32_e32 v4, 1, v1
	v_cmp_ge_u32_e32 vcc, v3, v2
	v_add_u32_e32 v3, 1, v5
	s_nop 0
	v_cndmask_b32_e32 v1, v1, v4, vcc
	v_mul_lo_u32 v4, v2, v1
	v_add_u32_e32 v2, v4, v2
	v_cmp_ne_u32_e32 vcc, v3, v2
	s_and_saveexec_b64 s[10:11], vcc
	s_xor_b64 s[10:11], exec, s[10:11]
	s_cbranch_execz .LBB0_367
	s_waitcnt lgkmcnt(0)
	s_add_u32 s38, s30, 0x4500
	s_addc_u32 s39, s31, 0
	v_mov_b32_e32 v0, 0
	global_load_dword v0, v0, s[38:39] sc1
	s_waitcnt vmcnt(0)
	v_cmp_eq_u32_e32 vcc, v0, v1
	s_and_saveexec_b64 s[26:27], vcc
	s_cbranch_execz .LBB0_366
	s_add_u32 s36, s30, 0x1200
	s_addc_u32 s37, s31, 0
	s_mov_b32 s50, 1
	s_mov_b64 s[40:41], 0
	v_mov_b32_e32 v0, 0
	s_branch .LBB0_357

.LBB0_621:
	s_or_b64 exec, exec, s[12:13]
	v_cvt_f32_u32_e32 v4, v2
	s_waitcnt vmcnt(0)
	buffer_inv sc1
	v_readfirstlane_b32 s10, v3
	v_sub_u32_e32 v3, 0, v2
	v_rcp_iflag_f32_e32 v4, v4
	v_add_u32_e32 v5, s10, v1
	v_mul_f32_e32 v4, 0x4f7ffffe, v4
	v_cvt_u32_f32_e32 v4, v4
	v_mul_lo_u32 v1, v3, v4
	v_mul_hi_u32 v1, v4, v1
	v_add_u32_e32 v1, v4, v1
	v_mul_hi_u32 v1, v5, v1
	v_mul_lo_u32 v3, v1, v2
	v_sub_u32_e32 v3, v5, v3
	v_add_u32_e32 v4, 1, v1
	v_cmp_ge_u32_e32 vcc, v3, v2
	s_nop 1
	v_cndmask_b32_e32 v1, v1, v4, vcc
	v_sub_u32_e32 v4, v3, v2
	v_cndmask_b32_e32 v3, v3, v4, vcc
	v_add_u32_e32 v4, 1, v1
	v_cmp_ge_u32_e32 vcc, v3, v2
	v_add_u32_e32 v3, 1, v5
	s_nop 0
	v_cndmask_b32_e32 v1, v1, v4, vcc
	v_mul_lo_u32 v4, v2, v1
	v_add_u32_e32 v2, v4, v2
	v_cmp_ne_u32_e32 vcc, v3, v2
	s_and_saveexec_b64 s[10:11], vcc
	s_xor_b64 s[10:11], exec, s[10:11]
	s_cbranch_execz .LBB0_635
	s_waitcnt lgkmcnt(0)
	s_add_u32 s16, s30, 0x4500
	s_addc_u32 s17, s31, 0
	v_mov_b32_e32 v0, 0
	global_load_dword v0, v0, s[16:17] sc1
	s_waitcnt vmcnt(0)
	v_cmp_eq_u32_e32 vcc, v0, v1
	s_and_saveexec_b64 s[12:13], vcc
	s_cbranch_execz .LBB0_634
	s_add_u32 s14, s30, 0x1200
	s_addc_u32 s15, s31, 0
	s_mov_b32 s40, 1
	s_mov_b64 s[18:19], 0
	v_mov_b32_e32 v0, 0
	s_branch .LBB0_625

.LBB0_634:
	s_or_b64 exec, exec, s[12:13]
	s_waitcnt vmcnt(0)
	s_waitcnt vmcnt(0)

.LBB0_652:
	s_or_b64 exec, exec, s[10:11]
	s_mov_b64 s[10:11], exec
	v_mbcnt_lo_u32_b32 v0, s10, 0
	v_mbcnt_hi_u32_b32 v0, s11, v0
	v_cmp_eq_u32_e32 vcc, 0, v0
	s_waitcnt vmcnt(0)
	s_and_saveexec_b64 s[12:13], vcc
	s_cbranch_execz .LBB0_654
	s_bcnt1_i32_b64 s10, s[10:11]
	v_mov_b32_e32 v0, 0x2000
	v_mov_b32_e32 v1, s10
	global_atomic_add v0, v1, s[8:9] offset:1024

.LBB0_712:
	s_or_b64 exec, exec, s[14:15]
	v_cvt_f32_u32_e32 v4, v2
	s_waitcnt vmcnt(0)
	buffer_inv sc1
	v_readfirstlane_b32 s12, v3
	v_sub_u32_e32 v3, 0, v2
	v_rcp_iflag_f32_e32 v4, v4
	v_add_u32_e32 v5, s12, v1
	v_mul_f32_e32 v4, 0x4f7ffffe, v4
	v_cvt_u32_f32_e32 v4, v4
	v_mul_lo_u32 v1, v3, v4
	v_mul_hi_u32 v1, v4, v1
	v_add_u32_e32 v1, v4, v1
	v_mul_hi_u32 v1, v5, v1
	v_mul_lo_u32 v3, v1, v2
	v_sub_u32_e32 v3, v5, v3
	v_add_u32_e32 v4, 1, v1
	v_cmp_ge_u32_e32 vcc, v3, v2
	s_nop 1
	v_cndmask_b32_e32 v1, v1, v4, vcc
	v_sub_u32_e32 v4, v3, v2
	v_cndmask_b32_e32 v3, v3, v4, vcc
	v_add_u32_e32 v4, 1, v1
	v_cmp_ge_u32_e32 vcc, v3, v2
	v_add_u32_e32 v3, 1, v5
	s_nop 0
	v_cndmask_b32_e32 v1, v1, v4, vcc
	v_mul_lo_u32 v4, v2, v1
	v_add_u32_e32 v2, v4, v2
	v_cmp_ne_u32_e32 vcc, v3, v2
	s_and_saveexec_b64 s[12:13], vcc
	s_xor_b64 s[12:13], exec, s[12:13]
	s_cbranch_execz .LBB0_726
	s_waitcnt lgkmcnt(0)
	s_add_u32 s18, s30, 0x4500
	s_addc_u32 s19, s31, 0
	v_mov_b32_e32 v0, 0
	global_load_dword v0, v0, s[18:19] sc1
	s_waitcnt vmcnt(0)
	v_cmp_eq_u32_e32 vcc, v0, v1
	s_and_saveexec_b64 s[14:15], vcc
	s_cbranch_execz .LBB0_725
	s_add_u32 s16, s30, 0x1200
	s_addc_u32 s17, s31, 0
	s_mov_b32 s40, 1
	s_mov_b64 s[20:21], 0
	v_mov_b32_e32 v0, 0
	s_branch .LBB0_716

.LBB0_725:
	s_or_b64 exec, exec, s[14:15]
	s_waitcnt vmcnt(0)
	s_waitcnt vmcnt(0)

.LBB0_743:
	s_or_b64 exec, exec, s[12:13]
	s_mov_b64 s[12:13], exec
	v_mbcnt_lo_u32_b32 v0, s12, 0
	v_mbcnt_hi_u32_b32 v0, s13, v0
	v_cmp_eq_u32_e32 vcc, 0, v0
	s_waitcnt vmcnt(0)
	s_and_saveexec_b64 s[14:15], vcc
	s_cbranch_execz .LBB0_745
	s_bcnt1_i32_b64 s12, s[12:13]
	v_mov_b32_e32 v0, 0x2000
	v_mov_b32_e32 v1, s12
	global_atomic_add v0, v1, s[8:9] offset:1024

.LBB0_787:
	s_or_b64 exec, exec, s[12:13]
	v_cvt_f32_u32_e32 v4, v2
	s_waitcnt vmcnt(0)
	buffer_inv sc1
	v_readfirstlane_b32 s10, v3
	v_sub_u32_e32 v3, 0, v2
	v_rcp_iflag_f32_e32 v4, v4
	v_add_u32_e32 v5, s10, v1
	v_mul_f32_e32 v4, 0x4f7ffffe, v4
	v_cvt_u32_f32_e32 v4, v4
	v_mul_lo_u32 v1, v3, v4
	v_mul_hi_u32 v1, v4, v1
	v_add_u32_e32 v1, v4, v1
	v_mul_hi_u32 v1, v5, v1
	v_mul_lo_u32 v3, v1, v2
	v_sub_u32_e32 v3, v5, v3
	v_add_u32_e32 v4, 1, v1
	v_cmp_ge_u32_e32 vcc, v3, v2
	s_nop 1
	v_cndmask_b32_e32 v1, v1, v4, vcc
	v_sub_u32_e32 v4, v3, v2
	v_cndmask_b32_e32 v3, v3, v4, vcc
	v_add_u32_e32 v4, 1, v1
	v_cmp_ge_u32_e32 vcc, v3, v2
	v_add_u32_e32 v3, 1, v5
	s_nop 0
	v_cndmask_b32_e32 v1, v1, v4, vcc
	v_mul_lo_u32 v4, v2, v1
	v_add_u32_e32 v2, v4, v2
	v_cmp_ne_u32_e32 vcc, v3, v2
	s_and_saveexec_b64 s[10:11], vcc
	s_xor_b64 s[10:11], exec, s[10:11]
	s_cbranch_execz .LBB0_801
	s_waitcnt lgkmcnt(0)
	s_add_u32 s16, s30, 0x4500
	s_addc_u32 s17, s31, 0
	v_mov_b32_e32 v0, 0
	global_load_dword v0, v0, s[16:17] sc1
	s_waitcnt vmcnt(0)
	v_cmp_eq_u32_e32 vcc, v0, v1
	s_and_saveexec_b64 s[12:13], vcc
	s_cbranch_execz .LBB0_800
	s_add_u32 s14, s30, 0x1200
	s_addc_u32 s15, s31, 0
	s_mov_b32 s38, 1
	s_mov_b64 s[18:19], 0
	v_mov_b32_e32 v0, 0
	s_branch .LBB0_791

.LBB0_864:
	s_or_b64 exec, exec, s[8:9]
	v_cvt_f32_u32_e32 v4, v2
	s_waitcnt vmcnt(0)
	buffer_inv sc1
	v_readfirstlane_b32 s6, v3
	v_sub_u32_e32 v3, 0, v2
	v_rcp_iflag_f32_e32 v4, v4
	v_add_u32_e32 v5, s6, v1
	v_mul_f32_e32 v4, 0x4f7ffffe, v4
	v_cvt_u32_f32_e32 v4, v4
	v_mul_lo_u32 v1, v3, v4
	v_mul_hi_u32 v1, v4, v1
	v_add_u32_e32 v1, v4, v1
	v_mul_hi_u32 v1, v5, v1
	v_mul_lo_u32 v3, v1, v2
	v_sub_u32_e32 v3, v5, v3
	v_add_u32_e32 v4, 1, v1
	v_cmp_ge_u32_e32 vcc, v3, v2
	s_nop 1
	v_cndmask_b32_e32 v1, v1, v4, vcc
	v_sub_u32_e32 v4, v3, v2
	v_cndmask_b32_e32 v3, v3, v4, vcc
	v_add_u32_e32 v4, 1, v1
	v_cmp_ge_u32_e32 vcc, v3, v2
	v_add_u32_e32 v3, 1, v5
	s_nop 0
	v_cndmask_b32_e32 v1, v1, v4, vcc
	v_mul_lo_u32 v4, v2, v1
	v_add_u32_e32 v2, v4, v2
	v_cmp_ne_u32_e32 vcc, v3, v2
	s_and_saveexec_b64 s[6:7], vcc
	s_xor_b64 s[6:7], exec, s[6:7]
	s_cbranch_execz .LBB0_878
	s_waitcnt lgkmcnt(0)
	s_add_u32 s12, s30, 0x4500
	s_addc_u32 s13, s31, 0
	v_mov_b32_e32 v0, 0
	global_load_dword v0, v0, s[12:13] sc1
	s_waitcnt vmcnt(0)
	v_cmp_eq_u32_e32 vcc, v0, v1
	s_and_saveexec_b64 s[8:9], vcc
	s_cbranch_execz .LBB0_877
	s_add_u32 s10, s30, 0x1200
	s_addc_u32 s11, s31, 0
	s_mov_b32 s24, 1
	s_mov_b64 s[14:15], 0
	v_mov_b32_e32 v0, 0
	s_branch .LBB0_868

.LBB0_877:
	s_or_b64 exec, exec, s[8:9]
	s_waitcnt vmcnt(0)
	s_waitcnt vmcnt(0)

.LBB0_895:
	s_or_b64 exec, exec, s[6:7]
	s_mov_b64 s[6:7], exec
	v_mbcnt_lo_u32_b32 v0, s6, 0
	v_mbcnt_hi_u32_b32 v0, s7, v0
	v_cmp_eq_u32_e32 vcc, 0, v0
	s_waitcnt vmcnt(0)
	s_and_saveexec_b64 s[8:9], vcc
	s_cbranch_execz .LBB0_897
	s_bcnt1_i32_b64 s6, s[6:7]
	v_mov_b32_e32 v0, 0x2000
	v_mov_b32_e32 v1, s6
	global_atomic_add v0, v1, s[4:5] offset:1024
